# 7.5 packed->scalar: diff-attention row-sum v_pk_add_f32 chain between the P.V MFMAs split into two scalar v_add_f32 chains
# speedup vs baseline: 1.0028x; 1.0028x over previous
; __device__ __forceinline__ unsigned cvtpk(float lo, float hi) { f32x2_t v = {lo, hi}; bf16x2_t b = __builtin_convertvector(v, bf16x2_t); return __builtin_bit_cast(unsigned, b); }
; #define ATT_MMAG(F, dvb) do { _Pragma("unroll") for (int j = 0; j < 4; ++j) o[dvb] = __builtin_amdgcn_mfma_f32_32x32x16_bf16(F[j], pb[j >> 1][j & 1], o[dvb], 0, 0, 0); } while (0)
; template <bool DIFF> ...
;     ...
;             const float d0 = c0 - m_run, d1 = c1 - m_run;
;             float rs0 = 0.f, rs1 = 0.f;
; #pragma unroll
;             for (int r = 0; r < 16; ++r) { s0[r] = __builtin_amdgcn_exp2f(__builtin_fmaf(s0[r], sc2, d0)); s1[r] = __builtin_amdgcn_exp2f(__builtin_fmaf(s1[r], sc2, d1)); rs0 += s0[r]; rs1 += s1[r]; }
;             l_run += rs0 + rs1;
;             bf16x8 pb[2][2];
; #pragma unroll
;             for (int g = 0; g < 2; ++g) {
;                 u32x4 w0, w1;
;                 w0.x = cvtpk(s0[8 * g], s0[8 * g + 1]); w0.y = cvtpk(s0[8 * g + 2], s0[8 * g + 3]); w0.z = cvtpk(s0[8 * g + 4], s0[8 * g + 5]); w0.w = cvtpk(s0[8 * g + 6], s0[8 * g + 7]);
;                 w1.x = cvtpk(s1[8 * g], s1[8 * g + 1]); w1.y = cvtpk(s1[8 * g + 2], s1[8 * g + 3]); w1.z = cvtpk(s1[8 * g + 4], s1[8 * g + 5]); w1.w = cvtpk(s1[8 * g + 6], s1[8 * g + 7]);
;                 pb[0][g] = __builtin_bit_cast(bf16x8, w0); pb[1][g] = __builtin_bit_cast(bf16x8, w1);
;             }
;             __builtin_amdgcn_sched_barrier(0);
;             ATT_MMAG(fa, 0); ATT_LOADG(fa, 2); __builtin_amdgcn_sched_barrier(0); ATT_MMAG(fb, 1); ATT_LOADG(fb, 3); __builtin_amdgcn_sched_barrier(0); ATT_MMAG(fa, 2); ATT_MMAG(fb, 3);
.LBB0_112:
	v_sub_f32_e32 v227, v213, v209
	v_sub_f32_e32 v226, v212, v209
	v_fmamk_f32 v98, v98, 0x3e38aa3b, v226
	v_fmamk_f32 v99, v99, 0x3e38aa3b, v226
	v_fmamk_f32 v100, v100, 0x3e38aa3b, v226
	v_fmamk_f32 v101, v101, 0x3e38aa3b, v226
	v_fmamk_f32 v102, v102, 0x3e38aa3b, v226
	v_fmamk_f32 v103, v103, 0x3e38aa3b, v226
	v_fmamk_f32 v104, v104, 0x3e38aa3b, v226
	v_fmamk_f32 v105, v105, 0x3e38aa3b, v226
	v_exp_f32_e32 v98, v98
	v_exp_f32_e32 v99, v99
	v_exp_f32_e32 v100, v100
	v_exp_f32_e32 v101, v101
	v_exp_f32_e32 v102, v102
	v_exp_f32_e32 v103, v103
	v_exp_f32_e32 v104, v104
	v_exp_f32_e32 v105, v105
	v_add_f32_e32 v212, v98, v100
	v_add_f32_e32 v213, v99, v101
	v_add_f32_e32 v212, v212, v102
	v_add_f32_e32 v213, v213, v103
	v_add_f32_e32 v212, v212, v104
	v_add_f32_e32 v213, v213, v105
	v_cvt_pk_bf16_f32 v98, v98, v99
	v_cvt_pk_bf16_f32 v99, v100, v101
	v_cvt_pk_bf16_f32 v100, v102, v103
	v_cvt_pk_bf16_f32 v101, v104, v105
	s_waitcnt lgkmcnt(8)
	s_nop 1
	v_mfma_f32_32x32x16_bf16 v[50:65], v[130:133], v[98:101], v[50:65]
	v_fmamk_f32 v106, v106, 0x3e38aa3b, v226
	v_fmamk_f32 v107, v107, 0x3e38aa3b, v226
	v_fmamk_f32 v108, v108, 0x3e38aa3b, v226
	v_fmamk_f32 v109, v109, 0x3e38aa3b, v226
	v_fmamk_f32 v110, v110, 0x3e38aa3b, v226
	v_fmamk_f32 v111, v111, 0x3e38aa3b, v226
	v_fmamk_f32 v112, v112, 0x3e38aa3b, v226
	v_mfma_f32_32x32x16_bf16 v[34:49], v[134:137], v[98:101], v[34:49]
	v_fmamk_f32 v113, v113, 0x3e38aa3b, v226
	v_exp_f32_e32 v106, v106
	v_exp_f32_e32 v107, v107
	v_exp_f32_e32 v108, v108
	v_exp_f32_e32 v109, v109
	v_exp_f32_e32 v110, v110
	v_exp_f32_e32 v111, v111
	v_mfma_f32_32x32x16_bf16 v[18:33], v[138:141], v[98:101], v[18:33]
	v_exp_f32_e32 v112, v112
	v_exp_f32_e32 v113, v113
	v_add_f32_e32 v212, v212, v106
	v_add_f32_e32 v213, v213, v107
	v_add_f32_e32 v212, v212, v108
	v_add_f32_e32 v213, v213, v109
	v_add_f32_e32 v212, v212, v110
	v_add_f32_e32 v213, v213, v111
	v_add_f32_e32 v212, v212, v112
	v_add_f32_e32 v213, v213, v113
	v_cvt_pk_bf16_f32 v106, v106, v107
	v_mfma_f32_32x32x16_bf16 v[2:17], v[142:145], v[98:101], v[2:17]
	ds_read_b64_tr_b16 v[130:131], v228 offset:24576
	ds_read_b64_tr_b16 v[132:133], v229 offset:26624
	ds_read_b64_tr_b16 v[134:135], v230 offset:24576
	ds_read_b64_tr_b16 v[136:137], v231 offset:26624
	ds_read_b64_tr_b16 v[138:139], v232 offset:24576
	ds_read_b64_tr_b16 v[140:141], v233 offset:26624
	ds_read_b64_tr_b16 v[142:143], v234 offset:24576
	ds_read_b64_tr_b16 v[144:145], v235 offset:26624
	v_cvt_pk_bf16_f32 v107, v108, v109
	v_cvt_pk_bf16_f32 v108, v110, v111
	v_cvt_pk_bf16_f32 v109, v112, v113
	s_waitcnt lgkmcnt(8)
	s_nop 1
	v_mfma_f32_32x32x16_bf16 v[50:65], v[146:149], v[106:109], v[50:65]
	v_fmamk_f32 v82, v82, 0x3e38aa3b, v227
	v_fmamk_f32 v83, v83, 0x3e38aa3b, v227
	v_fmamk_f32 v84, v84, 0x3e38aa3b, v227
	v_fmamk_f32 v85, v85, 0x3e38aa3b, v227
	v_fmamk_f32 v86, v86, 0x3e38aa3b, v227
	v_fmamk_f32 v87, v87, 0x3e38aa3b, v227
	v_fmamk_f32 v88, v88, 0x3e38aa3b, v227
	v_mfma_f32_32x32x16_bf16 v[34:49], v[150:153], v[106:109], v[34:49]
	v_fmamk_f32 v89, v89, 0x3e38aa3b, v227
	v_exp_f32_e32 v82, v82
	v_exp_f32_e32 v83, v83
	v_exp_f32_e32 v84, v84
	v_exp_f32_e32 v85, v85
	v_exp_f32_e32 v86, v86
	v_exp_f32_e32 v87, v87
	v_mfma_f32_32x32x16_bf16 v[18:33], v[154:157], v[106:109], v[18:33]
	v_exp_f32_e32 v88, v88
	v_exp_f32_e32 v89, v89
	v_add_f32_e32 v212, v212, v82
	v_add_f32_e32 v213, v213, v83
	v_add_f32_e32 v212, v212, v84
	v_add_f32_e32 v213, v213, v85
	v_add_f32_e32 v212, v212, v86
	v_add_f32_e32 v213, v213, v87
	v_add_f32_e32 v212, v212, v88
	v_add_f32_e32 v213, v213, v89
	v_cvt_pk_bf16_f32 v82, v82, v83
	v_mfma_f32_32x32x16_bf16 v[2:17], v[158:161], v[106:109], v[2:17]
	ds_read_b64_tr_b16 v[146:147], v228 offset:28672
	ds_read_b64_tr_b16 v[148:149], v229 offset:30720
	ds_read_b64_tr_b16 v[150:151], v230 offset:28672
	ds_read_b64_tr_b16 v[152:153], v231 offset:30720
	ds_read_b64_tr_b16 v[154:155], v232 offset:28672
	ds_read_b64_tr_b16 v[156:157], v233 offset:30720
	ds_read_b64_tr_b16 v[158:159], v234 offset:28672
	ds_read_b64_tr_b16 v[160:161], v235 offset:30720
	v_cvt_pk_bf16_f32 v83, v84, v85
	v_cvt_pk_bf16_f32 v84, v86, v87
	v_cvt_pk_bf16_f32 v85, v88, v89
	s_waitcnt lgkmcnt(8)
	s_nop 1
	v_mfma_f32_32x32x16_bf16 v[50:65], v[130:133], v[82:85], v[50:65]
	v_fmamk_f32 v90, v90, 0x3e38aa3b, v227
	v_fmamk_f32 v91, v91, 0x3e38aa3b, v227
	v_fmamk_f32 v92, v92, 0x3e38aa3b, v227
	v_fmamk_f32 v93, v93, 0x3e38aa3b, v227
	v_fmamk_f32 v94, v94, 0x3e38aa3b, v227
	v_fmamk_f32 v95, v95, 0x3e38aa3b, v227
	v_fmamk_f32 v96, v96, 0x3e38aa3b, v227
	v_mfma_f32_32x32x16_bf16 v[34:49], v[134:137], v[82:85], v[34:49]
	v_fmamk_f32 v97, v97, 0x3e38aa3b, v227
	v_exp_f32_e32 v90, v90
	v_exp_f32_e32 v91, v91
	v_exp_f32_e32 v92, v92
	v_exp_f32_e32 v93, v93
	v_exp_f32_e32 v94, v94
	v_exp_f32_e32 v95, v95
	v_mfma_f32_32x32x16_bf16 v[18:33], v[138:141], v[82:85], v[18:33]
	v_exp_f32_e32 v96, v96
	v_exp_f32_e32 v97, v97
	v_add_f32_e32 v212, v212, v90
	v_add_f32_e32 v213, v213, v91
	v_add_f32_e32 v212, v212, v92
	v_add_f32_e32 v213, v213, v93
	v_add_f32_e32 v212, v212, v94
	v_add_f32_e32 v213, v213, v95
	v_add_f32_e32 v212, v212, v96
	v_add_f32_e32 v213, v213, v97
	v_cvt_pk_bf16_f32 v90, v90, v91
	v_mfma_f32_32x32x16_bf16 v[2:17], v[142:145], v[82:85], v[2:17]
	v_cvt_pk_bf16_f32 v91, v92, v93
	v_cvt_pk_bf16_f32 v92, v94, v95
	v_cvt_pk_bf16_f32 v93, v96, v97
	s_waitcnt lgkmcnt(0)
	s_nop 1
	v_mfma_f32_32x32x16_bf16 v[50:65], v[146:149], v[90:93], v[50:65]
	v_mfma_f32_32x32x16_bf16 v[34:49], v[150:153], v[90:93], v[34:49]
	v_mfma_f32_32x32x16_bf16 v[18:33], v[154:157], v[90:93], v[18:33]
	v_mfma_f32_32x32x16_bf16 v[2:17], v[158:161], v[90:93], v[2:17]
	v_add_f32_e32 v212, v212, v213
	s_nop 0
	v_add_f32_e32 v205, v205, v212
